# scan pass 2 carry-in chain: 32 chunk-summary loads per 16-step trip issued up front (was load-wait-fma serialized per step), same fma order
# speedup vs baseline: 1.0224x; 1.0081x over previous
.LBB0_432:
	s_and_b32 s36, s25, 0x400
	s_ashr_i32 s37, s59, 31
	v_add_u32_e32 v2, s36, v44
	s_ashr_i32 s36, s59, 1
	s_lshr_b32 s37, s37, 27
	s_add_i32 s37, s36, s37
	s_ashr_i32 s60, s37, 5
	s_andn2_b32 s37, s37, 31
	s_sub_i32 s61, s36, s37
	s_lshl_b32 s36, s59, 10
	s_and_b32 s36, s36, 0x400
	v_ashrrev_i32_e32 v3, 31, v2
	v_add_u32_e32 v6, s36, v44
	v_lshlrev_b64 v[4:5], 2, v[2:3]
	s_cmp_lt_i32 s61, 1
	v_ashrrev_i32_e32 v7, 31, v6
	s_cbranch_scc1 .LBB0_437
	s_lshl_b32 s62, s61, 2
	s_lshl_b32 s36, s60, 7
	s_cmp_lt_u32 s62, 16
	s_cbranch_scc1 .LBB0_438
	s_ashr_i32 s37, s36, 31
	s_and_b32 s63, s62, 0x7ffffff0
	s_lshl_b64 s[38:39], s[36:37], 13
	s_add_u32 s38, s2, s38
	s_addc_u32 s39, s3, s39
	v_mov_b32_e32 v32, 0
	v_lshl_add_u64 v[8:9], s[38:39], 0, v[4:5]
	s_mov_b32 s37, 0
	v_mov_b32_e32 v33, v32
	v_lshlrev_b32_e32 v95, 2, v6
.LBB0_435:
	s_add_i32 s38, s36, s37
	s_ashr_i32 s39, s38, 31
	s_lshl_b64 s[38:39], s[38:39], 13
	s_add_u32 s64, s6, s38
	s_addc_u32 s65, s7, s39
	s_add_u32 s38, s4, s38
	s_addc_u32 s39, s5, s39
	s_add_i32 s37, s37, 16
	global_load_dwordx2 v[96:97], v95, s[38:39]
	global_load_dwordx2 v[98:99], v95, s[64:65]
	s_add_u32 s38, s38, 0x2000
	s_addc_u32 s39, s39, 0
	s_add_u32 s64, s64, 0x2000
	s_addc_u32 s65, s65, 0
	global_load_dwordx2 v[100:101], v95, s[38:39]
	global_load_dwordx2 v[102:103], v95, s[64:65]
	s_add_u32 s38, s38, 0x2000
	s_addc_u32 s39, s39, 0
	s_add_u32 s64, s64, 0x2000
	s_addc_u32 s65, s65, 0
	global_load_dwordx2 v[104:105], v95, s[38:39]
	global_load_dwordx2 v[106:107], v95, s[64:65]
	s_add_u32 s38, s38, 0x2000
	s_addc_u32 s39, s39, 0
	s_add_u32 s64, s64, 0x2000
	s_addc_u32 s65, s65, 0
	global_load_dwordx2 v[108:109], v95, s[38:39]
	global_load_dwordx2 v[110:111], v95, s[64:65]
	s_add_u32 s38, s38, 0x2000
	s_addc_u32 s39, s39, 0
	s_add_u32 s64, s64, 0x2000
	s_addc_u32 s65, s65, 0
	global_load_dwordx2 v[112:113], v95, s[38:39]
	global_load_dwordx2 v[114:115], v95, s[64:65]
	s_add_u32 s38, s38, 0x2000
	s_addc_u32 s39, s39, 0
	s_add_u32 s64, s64, 0x2000
	s_addc_u32 s65, s65, 0
	global_load_dwordx2 v[116:117], v95, s[38:39]
	global_load_dwordx2 v[118:119], v95, s[64:65]
	s_add_u32 s38, s38, 0x2000
	s_addc_u32 s39, s39, 0
	s_add_u32 s64, s64, 0x2000
	s_addc_u32 s65, s65, 0
	global_load_dwordx2 v[120:121], v95, s[38:39]
	global_load_dwordx2 v[122:123], v95, s[64:65]
	s_add_u32 s38, s38, 0x2000
	s_addc_u32 s39, s39, 0
	s_add_u32 s64, s64, 0x2000
	s_addc_u32 s65, s65, 0
	global_load_dwordx2 v[124:125], v95, s[38:39]
	global_load_dwordx2 v[126:127], v95, s[64:65]
	s_add_u32 s38, s38, 0x2000
	s_addc_u32 s39, s39, 0
	s_add_u32 s64, s64, 0x2000
	s_addc_u32 s65, s65, 0
	global_load_dwordx2 v[128:129], v95, s[38:39]
	global_load_dwordx2 v[130:131], v95, s[64:65]
	s_add_u32 s38, s38, 0x2000
	s_addc_u32 s39, s39, 0
	s_add_u32 s64, s64, 0x2000
	s_addc_u32 s65, s65, 0
	global_load_dwordx2 v[132:133], v95, s[38:39]
	global_load_dwordx2 v[134:135], v95, s[64:65]
	s_add_u32 s38, s38, 0x2000
	s_addc_u32 s39, s39, 0
	s_add_u32 s64, s64, 0x2000
	s_addc_u32 s65, s65, 0
	global_load_dwordx2 v[136:137], v95, s[38:39]
	global_load_dwordx2 v[138:139], v95, s[64:65]
	s_add_u32 s38, s38, 0x2000
	s_addc_u32 s39, s39, 0
	s_add_u32 s64, s64, 0x2000
	s_addc_u32 s65, s65, 0
	global_load_dwordx2 v[140:141], v95, s[38:39]
	global_load_dwordx2 v[142:143], v95, s[64:65]
	s_add_u32 s38, s38, 0x2000
	s_addc_u32 s39, s39, 0
	s_add_u32 s64, s64, 0x2000
	s_addc_u32 s65, s65, 0
	global_load_dwordx2 v[144:145], v95, s[38:39]
	global_load_dwordx2 v[146:147], v95, s[64:65]
	s_add_u32 s38, s38, 0x2000
	s_addc_u32 s39, s39, 0
	s_add_u32 s64, s64, 0x2000
	s_addc_u32 s65, s65, 0
	global_load_dwordx2 v[148:149], v95, s[38:39]
	global_load_dwordx2 v[150:151], v95, s[64:65]
	s_add_u32 s38, s38, 0x2000
	s_addc_u32 s39, s39, 0
	s_add_u32 s64, s64, 0x2000
	s_addc_u32 s65, s65, 0
	global_load_dwordx2 v[152:153], v95, s[38:39]
	global_load_dwordx2 v[154:155], v95, s[64:65]
	s_add_u32 s38, s38, 0x2000
	s_addc_u32 s39, s39, 0
	s_add_u32 s64, s64, 0x2000
	s_addc_u32 s65, s65, 0
	global_load_dwordx2 v[156:157], v95, s[38:39]
	global_load_dwordx2 v[158:159], v95, s[64:65]
	s_waitcnt vmcnt(30)
	v_pk_fma_f32 v[10:11], v[32:33], v[96:97], v[98:99]
	s_waitcnt vmcnt(28)
	v_pk_fma_f32 v[10:11], v[10:11], v[100:101], v[102:103]
	s_waitcnt vmcnt(26)
	v_pk_fma_f32 v[10:11], v[10:11], v[104:105], v[106:107]
	s_waitcnt vmcnt(24)
	v_pk_fma_f32 v[10:11], v[10:11], v[108:109], v[110:111]
	s_waitcnt vmcnt(22)
	v_pk_fma_f32 v[10:11], v[10:11], v[112:113], v[114:115]
	s_waitcnt vmcnt(20)
	v_pk_fma_f32 v[10:11], v[10:11], v[116:117], v[118:119]
	s_waitcnt vmcnt(18)
	v_pk_fma_f32 v[10:11], v[10:11], v[120:121], v[122:123]
	s_waitcnt vmcnt(16)
	v_pk_fma_f32 v[10:11], v[10:11], v[124:125], v[126:127]
	s_waitcnt vmcnt(14)
	v_pk_fma_f32 v[10:11], v[10:11], v[128:129], v[130:131]
	s_waitcnt vmcnt(12)
	v_pk_fma_f32 v[10:11], v[10:11], v[132:133], v[134:135]
	s_waitcnt vmcnt(10)
	v_pk_fma_f32 v[10:11], v[10:11], v[136:137], v[138:139]
	s_waitcnt vmcnt(8)
	v_pk_fma_f32 v[10:11], v[10:11], v[140:141], v[142:143]
	s_waitcnt vmcnt(6)
	v_pk_fma_f32 v[10:11], v[10:11], v[144:145], v[146:147]
	s_waitcnt vmcnt(4)
	v_pk_fma_f32 v[10:11], v[10:11], v[148:149], v[150:151]
	s_waitcnt vmcnt(2)
	v_pk_fma_f32 v[10:11], v[10:11], v[152:153], v[154:155]
	s_waitcnt vmcnt(0)
	v_pk_fma_f32 v[32:33], v[10:11], v[156:157], v[158:159]
	s_cmp_eq_u32 s63, s37
	s_cbranch_scc0 .LBB0_435
	s_and_b32 s37, s62, 12
	s_cmp_eq_u32 s37, 0
	s_cbranch_scc0 .LBB0_439
	s_branch .LBB0_441

.LBB0_439:
	s_add_i32 s38, s63, s36
	s_ashr_i32 s39, s38, 31
	s_lshl_b64 s[38:39], s[38:39], 13
	s_add_u32 s64, s6, s38
	s_addc_u32 s65, s7, s39
	s_add_u32 s38, s4, s38
	s_addc_u32 s39, s5, s39
	v_lshlrev_b32_e32 v95, 2, v6
.LBB0_440:
	global_load_dwordx2 v[96:97], v95, s[38:39]
	global_load_dwordx2 v[98:99], v95, s[64:65]
	s_add_u32 s38, s38, 0x2000
	s_addc_u32 s39, s39, 0
	s_add_u32 s64, s64, 0x2000
	s_addc_u32 s65, s65, 0
	global_load_dwordx2 v[100:101], v95, s[38:39]
	global_load_dwordx2 v[102:103], v95, s[64:65]
	s_add_u32 s38, s38, 0x2000
	s_addc_u32 s39, s39, 0
	s_add_u32 s64, s64, 0x2000
	s_addc_u32 s65, s65, 0
	global_load_dwordx2 v[104:105], v95, s[38:39]
	global_load_dwordx2 v[106:107], v95, s[64:65]
	s_add_u32 s38, s38, 0x2000
	s_addc_u32 s39, s39, 0
	s_add_u32 s64, s64, 0x2000
	s_addc_u32 s65, s65, 0
	global_load_dwordx2 v[108:109], v95, s[38:39]
	global_load_dwordx2 v[110:111], v95, s[64:65]
	s_add_u32 s38, s38, 0x2000
	s_addc_u32 s39, s39, 0
	s_add_u32 s64, s64, 0x2000
	s_addc_u32 s65, s65, 0
	s_add_i32 s37, s37, -4
	s_waitcnt vmcnt(6)
	v_pk_fma_f32 v[32:33], v[32:33], v[96:97], v[98:99]
	s_waitcnt vmcnt(4)
	v_pk_fma_f32 v[32:33], v[32:33], v[100:101], v[102:103]
	s_waitcnt vmcnt(2)
	v_pk_fma_f32 v[32:33], v[32:33], v[104:105], v[106:107]
	s_waitcnt vmcnt(0)
	v_pk_fma_f32 v[32:33], v[32:33], v[108:109], v[110:111]
	s_cmp_lg_u32 s37, 0
	s_cbranch_scc1 .LBB0_440
